# v24 plus q/k head-norm loop: rope-table loads issued together with the q/k and norm-weight loads (one memory round trip per item instead of two)
# baseline (speedup 1.0000x reference)
; __device__ __forceinline__ float bflo(unsigned w) { return __uint_as_float(w << 16); }
; __device__ __forceinline__ float bfhi(unsigned w) { return __uint_as_float(w & 0xffff0000u); }
; __device__ __forceinline__ void ew_phase(const Params& p, int l) {
;     ...
;         for (long it = grp; it < (long)ROWS * 20; it += ngrp) { const int row = (int)(it / 20), head = (int)(it % 20);
;             const bf16_t* src_ = P + (size_t)row * INC + (head < 16 ? OQ + head * 128 : OKK + (head - 16) * 128) + base;
;             bf16_t* dst_ = (head < 16) ? (P + (size_t)row * INC + OQ + head * 128 + base) : (KC + ((size_t)(head - 16) * ROWS + row) * 128 + base);
;             const float* gn = (head < 16 ? p.in[I_QN] : p.in[I_KN]) + (size_t)l * 128 + base;
;             const u32x2 wa = *(const u32x2*)src_, wb = *(const u32x2*)(src_ + 32);
;             const f32x4 ga = *(const f32x4*)gn, gb = *(const f32x4*)(gn + 32);
;             float a[4] = {bflo(wa.x), bfhi(wa.x), bflo(wa.y), bfhi(wa.y)}, b[4] = {bflo(wb.x), bfhi(wb.x), bflo(wb.y), bfhi(wb.y)};
;             float ss = 0.f;
; #pragma unroll
;             for (int q = 0; q < 4; ++q) ss += a[q] * a[q] + b[q] * b[q];
; #pragma unroll
;             for (int o = 8; o >= 1; o >>= 1) ss += __shfl_xor(ss, o);
;             const float rstd = rsqrtf(ss * (1.0f / 128.0f) + EPS);
; #pragma unroll
;             for (int q = 0; q < 4; ++q) { a[q] = a[q] * rstd * ga[q]; b[q] = b[q] * rstd * gb[q]; }
;             if (row >= CTX) { const int tk = row - CTX, pos = (t & 8) ? (tk & 63) : (tk >> 6);
;                 const f32x4 r01 = *(const f32x4*)(rope + pos * 32 + fi), r23 = *(const f32x4*)(rope + pos * 32 + fi + 2);
;                 const float cs[4] = {r01[0], r01[2], r23[0], r23[2]}, sn[4] = {r01[1], r01[3], r23[1], r23[3]};
; #pragma unroll
;                 for (int q = 0; q < 4; ++q) { const float x0 = a[q], x1 = b[q]; a[q] = x0 * cs[q] - x1 * sn[q]; b[q] = x0 * sn[q] + x1 * cs[q]; } }
.LBB0_251:
	s_or_b64 exec, exec, s[16:17]
	v_readlane_b32 s0, v245, 45
	v_lshlrev_b32_e32 v96, 1, v4
	v_readlane_b32 s1, v245, 46
	v_lshl_add_u64 v[14:15], v[14:15], 0, v[96:97]
	s_nop 0
	v_lshl_add_u64 v[16:17], v[18:19], 0, s[0:1]
	v_lshlrev_b32_e32 v18, 2, v4
	v_mov_b32_e32 v19, v97
	v_lshl_add_u64 v[16:17], v[16:17], 0, v[18:19]
	flat_load_dwordx2 v[18:19], v[14:15]
	s_nop 0
	flat_load_dwordx2 v[14:15], v[14:15] offset:64
	s_nop 0
	global_load_dwordx4 v[28:31], v[16:17], off
	global_load_dwordx4 v[32:35], v[16:17], off offset:128
	s_mov_b64 s[98:99], 0x13ff
	v_cmp_lt_i64_e64 s[98:99], s[98:99], v[2:3]
	s_and_saveexec_b64 s[100:101], s[98:99]
	v_add_u32_e32 v209, 0xffffff00, v12
	v_and_b32_e32 v208, 63, v12
	v_lshrrev_b32_e32 v209, 6, v209
	v_cndmask_b32_e32 v208, v208, v209, vcc
	v_lshlrev_b32_e32 v208, 5, v208
	v_mov_b32_e32 v209, v97
	v_lshl_add_u64 v[208:209], v[208:209], 3, v[6:7]
	flat_load_dwordx4 v[200:203], v[208:209]
	flat_load_dwordx4 v[204:207], v[208:209] offset:16
	s_mov_b64 exec, s[100:101]
	s_mov_b32 s0, 0x800000
	s_waitcnt vmcnt(0) lgkmcnt(0)
	v_lshlrev_b32_e32 v20, 16, v18
	v_and_b32_e32 v21, 0xffff0000, v14
	v_lshlrev_b32_e32 v16, 16, v14
	v_and_b32_e32 v17, 0xffff0000, v18
	v_pk_mul_f32 v[24:25], v[20:21], v[20:21]
	v_lshlrev_b32_e32 v38, 16, v15
	v_and_b32_e32 v39, 0xffff0000, v19
	v_pk_fma_f32 v[24:25], v[16:17], v[16:17], v[24:25]
	v_lshlrev_b32_e32 v14, 16, v19
	v_and_b32_e32 v15, 0xffff0000, v15
	v_pk_mul_f32 v[18:19], v[38:39], v[38:39]
	v_add_f32_e32 v13, v24, v25
	v_pk_fma_f32 v[18:19], v[14:15], v[14:15], v[18:19]
	v_mov_b32_e32 v22, v16
	v_add_f32_e32 v13, v18, v13
	v_add_f32_e32 v13, v19, v13
	ds_bpermute_b32 v18, v5, v13
	v_mov_b32_e32 v23, v21
	v_mov_b32_e32 v36, v32
	v_mov_b32_e32 v37, v29
	v_mov_b32_e32 v29, v33
	s_waitcnt lgkmcnt(0)
	v_add_f32_e32 v13, v13, v18
	ds_bpermute_b32 v18, v9, v13
	v_mov_b32_e32 v40, v38
	v_mov_b32_e32 v41, v15
	s_waitcnt lgkmcnt(0)
	v_add_f32_e32 v13, v13, v18
	ds_bpermute_b32 v18, v26, v13
	s_waitcnt lgkmcnt(0)
	v_add_f32_e32 v13, v13, v18
	ds_bpermute_b32 v18, v27, v13
	s_waitcnt lgkmcnt(0)
	v_add_f32_e32 v13, v13, v18
	v_fmamk_f32 v13, v13, 0x3c000000, v193
	v_cmp_gt_f32_e64 s[0:1], s0, v13
	v_mul_f32_e32 v18, 0x4b800000, v13
	s_nop 0
	v_cndmask_b32_e64 v13, v13, v18, s[0:1]
	v_rsq_f32_e32 v13, v13
	s_nop 0
	v_mul_f32_e32 v18, 0x45800000, v13
	v_cndmask_b32_e64 v24, v13, v18, s[0:1]
	v_pk_mul_f32 v[18:19], v[24:25], v[20:21] op_sel_hi:[0,1]
	v_pk_mul_f32 v[16:17], v[24:25], v[16:17] op_sel_hi:[0,1]
	v_pk_mul_f32 v[42:43], v[24:25], v[22:23] op_sel_hi:[0,1]
	v_pk_mul_f32 v[22:23], v[36:37], v[16:17]
	v_pk_mul_f32 v[20:21], v[28:29], v[18:19]
	v_pk_mul_f32 v[14:15], v[24:25], v[14:15] op_sel_hi:[0,1]
	v_pk_mul_f32 v[16:17], v[24:25], v[38:39] op_sel_hi:[0,1]
	v_pk_mul_f32 v[24:25], v[24:25], v[40:41] op_sel_hi:[0,1]
	v_mov_b32_e32 v28, v34
	v_mov_b32_e32 v29, v31
	v_mov_b32_e32 v31, v35
	s_mov_b64 s[0:1], 0x13ff
	v_pk_mul_f32 v[18:19], v[32:33], v[42:43]
	v_pk_mul_f32 v[16:17], v[28:29], v[16:17]
	v_pk_mul_f32 v[14:15], v[30:31], v[14:15]
	v_pk_mul_f32 v[24:25], v[34:35], v[24:25]
	v_cmp_lt_i64_e64 s[0:1], s[0:1], v[2:3]
	s_and_saveexec_b64 s[16:17], s[0:1]
	s_cbranch_execz .LBB0_248
	v_mov_b32_e32 v36, v22
	v_mov_b32_e32 v37, v21
	v_mov_b32_e32 v18, v20
	v_mov_b32_e32 v19, v23
	v_mov_b32_e32 v24, v14
	v_mov_b32_e32 v25, v17
	s_waitcnt vmcnt(0) lgkmcnt(0)
	v_mov_b32_e32 v38, v201
	v_mov_b32_e32 v39, v203
	v_mov_b32_e32 v12, v200
	v_mov_b32_e32 v13, v202
	v_pk_mul_f32 v[36:37], v[36:37], v[38:39]
	s_nop 0
	v_pk_fma_f32 v[12:13], v[18:19], v[12:13], v[36:37] neg_lo:[0,0,1] neg_hi:[0,0,1]
	v_mov_b32_e32 v18, v200
	v_mov_b32_e32 v19, v203
	v_pk_mul_f32 v[18:19], v[22:23], v[18:19]
	v_mov_b32_e32 v22, v201
	v_mov_b32_e32 v23, v202
	v_pk_fma_f32 v[18:19], v[20:21], v[22:23], v[18:19]
	v_mov_b32_e32 v22, v16
	v_mov_b32_e32 v23, v15
	v_mov_b32_e32 v200, v205
	v_mov_b32_e32 v201, v207
	v_mov_b32_e32 v20, v204
	v_mov_b32_e32 v21, v206
	v_pk_mul_f32 v[22:23], v[22:23], v[200:201]
	s_nop 0
	v_pk_fma_f32 v[200:201], v[24:25], v[20:21], v[22:23] neg_lo:[0,0,1] neg_hi:[0,0,1]
	v_mov_b32_e32 v21, v207
	v_pk_mul_f32 v[16:17], v[16:17], v[20:21]
	v_mov_b32_e32 v20, v205
	v_mov_b32_e32 v21, v206
	v_pk_fma_f32 v[24:25], v[14:15], v[20:21], v[16:17]
	v_mov_b32_e32 v20, v12
	v_mov_b32_e32 v23, v13
	v_mov_b32_e32 v14, v200
	v_mov_b32_e32 v17, v201
	s_branch .LBB0_248

; __global__ void __launch_bounds__(NTHREADS, 2) mega_fwd(Params p0) {
	.amdhsa_kernel _Z8mega_fwd6Params
		.amdhsa_group_segment_fixed_size 0
		.amdhsa_private_segment_fixed_size 0
		.amdhsa_kernarg_size 416
		.amdhsa_user_sgpr_count 2
		.amdhsa_user_sgpr_dispatch_ptr 0
		.amdhsa_user_sgpr_queue_ptr 0
		.amdhsa_user_sgpr_kernarg_segment_ptr 1
		.amdhsa_user_sgpr_dispatch_id 0
		.amdhsa_user_sgpr_kernarg_preload_length 0
		.amdhsa_user_sgpr_kernarg_preload_offset 0
		.amdhsa_user_sgpr_private_segment_size 0
		.amdhsa_uses_dynamic_stack 0
		.amdhsa_enable_private_segment 0
		.amdhsa_system_sgpr_workgroup_id_x 1
		.amdhsa_system_sgpr_workgroup_id_y 0
		.amdhsa_system_sgpr_workgroup_id_z 0
		.amdhsa_system_sgpr_workgroup_info 0
		.amdhsa_system_vgpr_workitem_id 2
		.amdhsa_next_free_vgpr 248
		.amdhsa_next_free_sgpr 102
		.amdhsa_accum_offset 248
		.amdhsa_reserve_vcc 1
		.amdhsa_float_round_mode_32 0
		.amdhsa_float_round_mode_16_64 0
		.amdhsa_float_denorm_mode_32 3
		.amdhsa_float_denorm_mode_16_64 3
		.amdhsa_dx10_clamp 1
		.amdhsa_ieee_mode 1
		.amdhsa_fp16_overflow 0
		.amdhsa_tg_split 0
		.amdhsa_exception_fp_ieee_invalid_op 0
		.amdhsa_exception_fp_denorm_src 0
		.amdhsa_exception_fp_ieee_div_zero 0
		.amdhsa_exception_fp_ieee_overflow 0
		.amdhsa_exception_fp_ieee_underflow 0
		.amdhsa_exception_fp_ieee_inexact 0
		.amdhsa_exception_int_div_zero 0
	.end_amdhsa_kernel

; __global__ void __launch_bounds__(NTHREADS, 2) mega_fwd(Params p0) {
amdhsa.kernels:
  - .agpr_count:     0
    .args:
      - .offset:         0
        .size:           160
        .value_kind:     by_value
      - .offset:         160
        .size:           4
        .value_kind:     hidden_block_count_x
      - .offset:         164
        .size:           4
        .value_kind:     hidden_block_count_y
      - .offset:         168
        .size:           4
        .value_kind:     hidden_block_count_z
      - .offset:         172
        .size:           2
        .value_kind:     hidden_group_size_x
      - .offset:         174
        .size:           2
        .value_kind:     hidden_group_size_y
      - .offset:         176
        .size:           2
        .value_kind:     hidden_group_size_z
      - .offset:         178
        .size:           2
        .value_kind:     hidden_remainder_x
      - .offset:         180
        .size:           2
        .value_kind:     hidden_remainder_y
      - .offset:         182
        .size:           2
        .value_kind:     hidden_remainder_z
      - .offset:         200
        .size:           8
        .value_kind:     hidden_global_offset_x
      - .offset:         208
        .size:           8
        .value_kind:     hidden_global_offset_y
      - .offset:         216
        .size:           8
        .value_kind:     hidden_global_offset_z
      - .offset:         224
        .size:           2
        .value_kind:     hidden_grid_dims
      - .offset:         248
        .size:           8
        .value_kind:     hidden_multigrid_sync_arg
      - .offset:         280
        .size:           4
        .value_kind:     hidden_dynamic_lds_size
    .group_segment_fixed_size: 0
    .kernarg_segment_align: 8
    .kernarg_segment_size: 416
    .language:       OpenCL C
    .language_version:
      - 2
      - 0
    .max_flat_workgroup_size: 512
    .name:           _Z8mega_fwd6Params
    .private_segment_fixed_size: 0
    .sgpr_count:     108
    .sgpr_spill_count: 199
    .symbol:         _Z8mega_fwd6Params.kd
    .uniform_work_group_size: 1
    .uses_dynamic_stack: false
    .vgpr_count:     248
    .vgpr_spill_count: 0
    .wavefront_size: 64
